# SSD scan diagonal tiles: per-element exec-masked branches replaced by branch-free compare/select (32 sites), on top of shared-score version
# speedup vs baseline: 1.0128x; 1.0128x over previous
.LBB0_1746:
	v_max_f32_e32 v77, v77, v77
	v_max_f32_e32 v77, 0xda24260, v77
	v_rcp_f32_e32 v77, v77
	s_andn2_b64 vcc, exec, s[42:43]
	v_mul_f32_e32 v77, v1, v77
	s_cbranch_vccnz .LBB0_1780
	v_sub_f32_e32 v212, v76, v72
	v_cmp_gt_u32_e64 s[2:3], v86, v115
	v_min_f32_e32 v212, 0, v212
	v_cmp_eq_u32_e32 vcc, v115, v86
	v_exp_f32_e32 v212, v212
	v_add_f32_e32 v213, v77, v84
	v_mul_f32_e32 v212, v212, v84
	v_cndmask_b32_e64 v212, 0, v212, s[2:3]
	v_cndmask_b32_e32 v2, v212, v213, vcc
	v_sub_f32_e32 v214, v76, v73
	v_cmp_gt_u32_e64 s[2:3], v86, v129
	v_min_f32_e32 v214, 0, v214
	v_cmp_eq_u32_e32 vcc, v129, v86
	v_exp_f32_e32 v214, v214
	v_add_f32_e32 v215, v77, v85
	v_mul_f32_e32 v214, v214, v85
	v_cndmask_b32_e64 v214, 0, v214, s[2:3]
	v_cndmask_b32_e32 v3, v214, v215, vcc
	v_sub_f32_e32 v216, v76, v74
	v_cmp_gt_u32_e64 s[2:3], v86, v130
	v_min_f32_e32 v216, 0, v216
	v_cmp_eq_u32_e32 vcc, v130, v86
	v_exp_f32_e32 v216, v216
	v_add_f32_e32 v217, v77, v82
	v_mul_f32_e32 v216, v216, v82
	v_cndmask_b32_e64 v216, 0, v216, s[2:3]
	v_cndmask_b32_e32 v4, v216, v217, vcc
	v_sub_f32_e32 v218, v76, v75
	v_cmp_gt_u32_e64 s[2:3], v86, v131
	v_min_f32_e32 v218, 0, v218
	v_cmp_eq_u32_e32 vcc, v131, v86
	v_exp_f32_e32 v218, v218
	v_add_f32_e32 v219, v77, v83
	v_mul_f32_e32 v218, v218, v83
	v_cndmask_b32_e64 v218, 0, v218, s[2:3]
	v_cndmask_b32_e32 v5, v218, v219, vcc
	v_sub_f32_e32 v212, v76, v68
	v_cmp_gt_u32_e64 s[2:3], v86, v132
	v_min_f32_e32 v212, 0, v212
	v_cmp_eq_u32_e32 vcc, v132, v86
	v_exp_f32_e32 v212, v212
	v_add_f32_e32 v213, v77, v80
	v_mul_f32_e32 v212, v212, v80
	v_cndmask_b32_e64 v212, 0, v212, s[2:3]
	v_cndmask_b32_e32 v6, v212, v213, vcc
	v_sub_f32_e32 v214, v76, v69
	v_cmp_gt_u32_e64 s[2:3], v86, v133
	v_min_f32_e32 v214, 0, v214
	v_cmp_eq_u32_e32 vcc, v133, v86
	v_exp_f32_e32 v214, v214
	v_add_f32_e32 v215, v77, v81
	v_mul_f32_e32 v214, v214, v81
	v_cndmask_b32_e64 v214, 0, v214, s[2:3]
	v_cndmask_b32_e32 v7, v214, v215, vcc
	v_sub_f32_e32 v216, v76, v70
	v_cmp_gt_u32_e64 s[2:3], v86, v134
	v_min_f32_e32 v216, 0, v216
	v_cmp_eq_u32_e32 vcc, v134, v86
	v_exp_f32_e32 v216, v216
	v_add_f32_e32 v217, v77, v78
	v_mul_f32_e32 v216, v216, v78
	v_cndmask_b32_e64 v216, 0, v216, s[2:3]
	v_cndmask_b32_e32 v8, v216, v217, vcc
	v_sub_f32_e32 v218, v76, v71
	v_cmp_gt_u32_e64 s[2:3], v86, v135
	v_min_f32_e32 v218, 0, v218
	v_cmp_eq_u32_e32 vcc, v135, v86
	v_exp_f32_e32 v218, v218
	v_add_f32_e32 v219, v77, v79
	v_mul_f32_e32 v218, v218, v79
	v_cndmask_b32_e64 v218, 0, v218, s[2:3]
	v_cndmask_b32_e32 v9, v218, v219, vcc
.LBB0_1780:
	v_cvt_pk_bf16_f32 v2, v2, v3
	v_cvt_pk_bf16_f32 v3, v4, v5
	v_cvt_pk_bf16_f32 v4, v6, v7
	v_cvt_pk_bf16_f32 v5, v8, v9
	s_and_b64 vcc, exec, s[10:11]
	s_nop 0
	v_mfma_f32_16x16x32_bf16 v[2:5], v[24:27], v[2:5], 0
	s_cbranch_vccz .LBB0_1814
	ds_read_b128 v[68:71], v182 offset:128
	ds_read_b128 v[6:9], v182 offset:192
	v_lshlrev_b32_e32 v73, 16, v64
	s_waitcnt lgkmcnt(0)
	v_sub_f32_e32 v212, v76, v68
	v_cmp_gt_u32_e64 s[2:3], v86, v136
	v_min_f32_e32 v212, 0, v212
	v_cmp_eq_u32_e32 vcc, v136, v86
	v_exp_f32_e32 v212, v212
	v_add_f32_e32 v213, v77, v73
	v_mul_f32_e32 v212, v212, v73
	v_cndmask_b32_e64 v212, 0, v212, s[2:3]
	v_cndmask_b32_e32 v72, v212, v213, vcc
.LBB0_1785:
	s_waitcnt lgkmcnt(0)
	v_and_b32_e32 v68, 0xffff0000, v64
	v_sub_f32_e32 v214, v76, v69
	v_cmp_gt_u32_e64 s[2:3], v86, v137
	v_min_f32_e32 v214, 0, v214
	v_cmp_eq_u32_e32 vcc, v137, v86
	v_exp_f32_e32 v214, v214
	v_add_f32_e32 v215, v77, v68
	v_mul_f32_e32 v214, v214, v68
	v_cndmask_b32_e64 v214, 0, v214, s[2:3]
	v_cndmask_b32_e32 v64, v214, v215, vcc
	v_lshlrev_b32_e32 v68, 16, v65
	v_sub_f32_e32 v216, v76, v70
	v_cmp_gt_u32_e64 s[2:3], v86, v138
	v_min_f32_e32 v216, 0, v216
	v_cmp_eq_u32_e32 vcc, v138, v86
	v_exp_f32_e32 v216, v216
	v_add_f32_e32 v217, v77, v68
	v_mul_f32_e32 v216, v216, v68
	v_cndmask_b32_e64 v216, 0, v216, s[2:3]
	v_cndmask_b32_e32 v73, v216, v217, vcc
	v_and_b32_e32 v68, 0xffff0000, v65
	v_sub_f32_e32 v218, v76, v71
	v_cmp_gt_u32_e64 s[2:3], v86, v139
	v_min_f32_e32 v218, 0, v218
	v_cmp_eq_u32_e32 vcc, v139, v86
	v_exp_f32_e32 v218, v218
	v_add_f32_e32 v219, v77, v68
	v_mul_f32_e32 v218, v218, v68
	v_cndmask_b32_e64 v218, 0, v218, s[2:3]
	v_cndmask_b32_e32 v65, v218, v219, vcc
	v_lshlrev_b32_e32 v69, 16, v66
	v_sub_f32_e32 v212, v76, v6
	v_cmp_gt_u32_e64 s[2:3], v86, v140
	v_min_f32_e32 v212, 0, v212
	v_cmp_eq_u32_e32 vcc, v140, v86
	v_exp_f32_e32 v212, v212
	v_add_f32_e32 v213, v77, v69
	v_mul_f32_e32 v212, v212, v69
	v_cndmask_b32_e64 v212, 0, v212, s[2:3]
	v_cndmask_b32_e32 v68, v212, v213, vcc
	v_and_b32_e32 v6, 0xffff0000, v66
	v_sub_f32_e32 v214, v76, v7
	v_cmp_gt_u32_e64 s[2:3], v86, v141
	v_min_f32_e32 v214, 0, v214
	v_cmp_eq_u32_e32 vcc, v141, v86
	v_exp_f32_e32 v214, v214
	v_add_f32_e32 v215, v77, v6
	v_mul_f32_e32 v214, v214, v6
	v_cndmask_b32_e64 v214, 0, v214, s[2:3]
	v_cndmask_b32_e32 v66, v214, v215, vcc
	v_lshlrev_b32_e32 v6, 16, v67
	v_sub_f32_e32 v216, v76, v8
	v_cmp_gt_u32_e64 s[2:3], v86, v142
	v_min_f32_e32 v216, 0, v216
	v_cmp_eq_u32_e32 vcc, v142, v86
	v_exp_f32_e32 v216, v216
	v_add_f32_e32 v217, v77, v6
	v_mul_f32_e32 v216, v216, v6
	v_cndmask_b32_e64 v216, 0, v216, s[2:3]
	v_cndmask_b32_e32 v69, v216, v217, vcc
	v_and_b32_e32 v6, 0xffff0000, v67
	v_sub_f32_e32 v218, v76, v9
	v_cmp_gt_u32_e64 s[2:3], v86, v143
	v_min_f32_e32 v218, 0, v218
	v_cmp_eq_u32_e32 vcc, v143, v86
	v_exp_f32_e32 v218, v218
	v_add_f32_e32 v219, v77, v6
	v_mul_f32_e32 v218, v218, v6
	v_cndmask_b32_e64 v218, 0, v218, s[2:3]
	v_cndmask_b32_e32 v67, v218, v219, vcc
	v_cvt_pk_bf16_f32 v6, v72, v64
	v_cvt_pk_bf16_f32 v7, v73, v65
	v_cvt_pk_bf16_f32 v8, v68, v66
	v_cvt_pk_bf16_f32 v9, v69, v67
	s_nop 1
	v_mfma_f32_16x16x32_bf16 v[6:9], v[20:23], v[6:9], v[2:5]
	s_branch .LBB0_1816

.LBB0_1818:
	v_max_f32_e32 v117, v117, v117
	v_max_f32_e32 v117, 0xda24260, v117
	v_rcp_f32_e32 v117, v117
	s_andn2_b64 vcc, exec, s[72:73]
	v_mul_f32_e32 v117, v1, v117
	s_cbranch_vccnz .LBB0_1852
	s_waitcnt lgkmcnt(0)
	v_sub_f32_e32 v212, v116, v64
	v_cmp_gt_u32_e64 s[2:3], v183, v144
	v_min_f32_e32 v212, 0, v212
	v_cmp_eq_u32_e32 vcc, v144, v183
	v_exp_f32_e32 v212, v212
	v_add_f32_e32 v213, v117, v124
	v_mul_f32_e32 v212, v212, v124
	v_cndmask_b32_e64 v212, 0, v212, s[2:3]
	v_cndmask_b32_e32 v2, v212, v213, vcc
.LBB0_1823:
	s_waitcnt lgkmcnt(0)
	v_sub_f32_e32 v214, v116, v65
	v_cmp_gt_u32_e64 s[2:3], v183, v145
	v_min_f32_e32 v214, 0, v214
	v_cmp_eq_u32_e32 vcc, v145, v183
	v_exp_f32_e32 v214, v214
	v_add_f32_e32 v215, v117, v125
	v_mul_f32_e32 v214, v214, v125
	v_cndmask_b32_e64 v214, 0, v214, s[2:3]
	v_cndmask_b32_e32 v3, v214, v215, vcc
.LBB0_1827:
	s_waitcnt lgkmcnt(0)
	v_sub_f32_e32 v216, v116, v66
	v_cmp_gt_u32_e64 s[2:3], v183, v146
	v_min_f32_e32 v216, 0, v216
	v_cmp_eq_u32_e32 vcc, v146, v183
	v_exp_f32_e32 v216, v216
	v_add_f32_e32 v217, v117, v122
	v_mul_f32_e32 v216, v216, v122
	v_cndmask_b32_e64 v216, 0, v216, s[2:3]
	v_cndmask_b32_e32 v4, v216, v217, vcc
.LBB0_1831:
	s_waitcnt lgkmcnt(0)
	v_sub_f32_e32 v218, v116, v67
	v_cmp_gt_u32_e64 s[2:3], v183, v147
	v_min_f32_e32 v218, 0, v218
	v_cmp_eq_u32_e32 vcc, v147, v183
	v_exp_f32_e32 v218, v218
	v_add_f32_e32 v219, v117, v123
	v_mul_f32_e32 v218, v218, v123
	v_cndmask_b32_e64 v218, 0, v218, s[2:3]
	v_cndmask_b32_e32 v5, v218, v219, vcc
.LBB0_1835:
	s_waitcnt lgkmcnt(0)
	v_sub_f32_e32 v212, v116, v52
	v_cmp_gt_u32_e64 s[2:3], v183, v148
	v_min_f32_e32 v212, 0, v212
	v_cmp_eq_u32_e32 vcc, v148, v183
	v_exp_f32_e32 v212, v212
	v_add_f32_e32 v213, v117, v120
	v_mul_f32_e32 v212, v212, v120
	v_cndmask_b32_e64 v212, 0, v212, s[2:3]
	v_cndmask_b32_e32 v6, v212, v213, vcc
.LBB0_1839:
	s_waitcnt lgkmcnt(0)
	v_sub_f32_e32 v214, v116, v53
	v_cmp_gt_u32_e64 s[2:3], v183, v149
	v_min_f32_e32 v214, 0, v214
	v_cmp_eq_u32_e32 vcc, v149, v183
	v_exp_f32_e32 v214, v214
	v_add_f32_e32 v215, v117, v121
	v_mul_f32_e32 v214, v214, v121
	v_cndmask_b32_e64 v214, 0, v214, s[2:3]
	v_cndmask_b32_e32 v7, v214, v215, vcc
.LBB0_1843:
	s_waitcnt lgkmcnt(0)
	v_sub_f32_e32 v216, v116, v54
	v_cmp_gt_u32_e64 s[2:3], v183, v151
	v_min_f32_e32 v216, 0, v216
	v_cmp_eq_u32_e32 vcc, v151, v183
	v_exp_f32_e32 v216, v216
	v_add_f32_e32 v217, v117, v118
	v_mul_f32_e32 v216, v216, v118
	v_cndmask_b32_e64 v216, 0, v216, s[2:3]
	v_cndmask_b32_e32 v8, v216, v217, vcc
.LBB0_1847:
	s_waitcnt lgkmcnt(0)
	v_sub_f32_e32 v218, v116, v55
	v_cmp_gt_u32_e64 s[2:3], v183, v161
	v_min_f32_e32 v218, 0, v218
	v_cmp_eq_u32_e32 vcc, v161, v183
	v_exp_f32_e32 v218, v218
	v_add_f32_e32 v219, v117, v119
	v_mul_f32_e32 v218, v218, v119
	v_cndmask_b32_e64 v218, 0, v218, s[2:3]
	v_cndmask_b32_e32 v9, v218, v219, vcc
.LBB0_1851:
.LBB0_1852:
	v_cvt_pk_bf16_f32 v2, v2, v3
	v_cvt_pk_bf16_f32 v3, v4, v5
	v_cvt_pk_bf16_f32 v4, v6, v7
	v_cvt_pk_bf16_f32 v5, v8, v9
	s_and_b64 vcc, exec, s[42:43]
	s_nop 0
	v_mfma_f32_16x16x32_bf16 v[2:5], v[16:19], v[2:5], v[84:87]
	s_cbranch_vccnz .LBB0_1886
	s_nop 1
	ds_read_b128 v[84:87], v182 offset:384
	ds_read_b128 v[6:9], v182 offset:448
	v_lshlrev_b32_e32 v119, 16, v80
	s_waitcnt lgkmcnt(0)
	v_sub_f32_e32 v212, v116, v84
	v_cmp_gt_u32_e64 s[2:3], v183, v166
	v_min_f32_e32 v212, 0, v212
	v_cmp_eq_u32_e32 vcc, v166, v183
	v_exp_f32_e32 v212, v212
	v_add_f32_e32 v213, v117, v119
	v_mul_f32_e32 v212, v212, v119
	v_cndmask_b32_e64 v212, 0, v212, s[2:3]
	v_cndmask_b32_e32 v118, v212, v213, vcc
.LBB0_1857:
	s_waitcnt lgkmcnt(0)
	v_and_b32_e32 v84, 0xffff0000, v80
	v_sub_f32_e32 v214, v116, v85
	v_cmp_gt_u32_e64 s[2:3], v183, v167
	v_min_f32_e32 v214, 0, v214
	v_cmp_eq_u32_e32 vcc, v167, v183
	v_exp_f32_e32 v214, v214
	v_add_f32_e32 v215, v117, v84
	v_mul_f32_e32 v214, v214, v84
	v_cndmask_b32_e64 v214, 0, v214, s[2:3]
	v_cndmask_b32_e32 v80, v214, v215, vcc
	v_lshlrev_b32_e32 v84, 16, v81
	v_sub_f32_e32 v216, v116, v86
	v_cmp_gt_u32_e64 s[2:3], v183, v168
	v_min_f32_e32 v216, 0, v216
	v_cmp_eq_u32_e32 vcc, v168, v183
	v_exp_f32_e32 v216, v216
	v_add_f32_e32 v217, v117, v84
	v_mul_f32_e32 v216, v216, v84
	v_cndmask_b32_e64 v216, 0, v216, s[2:3]
	v_cndmask_b32_e32 v119, v216, v217, vcc
	v_and_b32_e32 v84, 0xffff0000, v81
	v_sub_f32_e32 v218, v116, v87
	v_cmp_gt_u32_e64 s[2:3], v183, v169
	v_min_f32_e32 v218, 0, v218
	v_cmp_eq_u32_e32 vcc, v169, v183
	v_exp_f32_e32 v218, v218
	v_add_f32_e32 v219, v117, v84
	v_mul_f32_e32 v218, v218, v84
	v_cndmask_b32_e64 v218, 0, v218, s[2:3]
	v_cndmask_b32_e32 v81, v218, v219, vcc
	v_lshlrev_b32_e32 v85, 16, v82
	v_sub_f32_e32 v212, v116, v6
	v_cmp_gt_u32_e64 s[2:3], v183, v170
	v_min_f32_e32 v212, 0, v212
	v_cmp_eq_u32_e32 vcc, v170, v183
	v_exp_f32_e32 v212, v212
	v_add_f32_e32 v213, v117, v85
	v_mul_f32_e32 v212, v212, v85
	v_cndmask_b32_e64 v212, 0, v212, s[2:3]
	v_cndmask_b32_e32 v84, v212, v213, vcc
	v_and_b32_e32 v6, 0xffff0000, v82
	v_sub_f32_e32 v214, v116, v7
	v_cmp_gt_u32_e64 s[2:3], v183, v171
	v_min_f32_e32 v214, 0, v214
	v_cmp_eq_u32_e32 vcc, v171, v183
	v_exp_f32_e32 v214, v214
	v_add_f32_e32 v215, v117, v6
	v_mul_f32_e32 v214, v214, v6
	v_cndmask_b32_e64 v214, 0, v214, s[2:3]
	v_cndmask_b32_e32 v82, v214, v215, vcc
	v_lshlrev_b32_e32 v6, 16, v83
	v_sub_f32_e32 v216, v116, v8
	v_cmp_gt_u32_e64 s[2:3], v183, v172
	v_min_f32_e32 v216, 0, v216
	v_cmp_eq_u32_e32 vcc, v172, v183
	v_exp_f32_e32 v216, v216
	v_add_f32_e32 v217, v117, v6
	v_mul_f32_e32 v216, v216, v6
	v_cndmask_b32_e64 v216, 0, v216, s[2:3]
	v_cndmask_b32_e32 v85, v216, v217, vcc
	v_and_b32_e32 v6, 0xffff0000, v83
	v_sub_f32_e32 v218, v116, v9
	v_cmp_gt_u32_e64 s[2:3], v183, v173
	v_min_f32_e32 v218, 0, v218
	v_cmp_eq_u32_e32 vcc, v173, v183
	v_exp_f32_e32 v218, v218
	v_add_f32_e32 v219, v117, v6
	v_mul_f32_e32 v218, v218, v6
	v_cndmask_b32_e64 v218, 0, v218, s[2:3]
	v_cndmask_b32_e32 v83, v218, v219, vcc
	v_cvt_pk_bf16_f32 v6, v118, v80
	v_cvt_pk_bf16_f32 v7, v119, v81
	v_cvt_pk_bf16_f32 v8, v84, v82
	v_cvt_pk_bf16_f32 v9, v85, v83
	s_nop 1
	v_mfma_f32_16x16x32_bf16 v[2:5], v[12:15], v[6:9], v[2:5]

.LBB0_1888:
	s_branch .Lmk_skip
	s_nop 0
	s_nop 0
	s_nop 0
	s_nop 0
	s_nop 0
	s_nop 0
	s_nop 0
	s_nop 0
	s_nop 0
	s_nop 0
	s_nop 0
	s_nop 0
	s_nop 0
	s_nop 0
	s_nop 0
	s_nop 0
	s_nop 0
	s_nop 0
	s_nop 0
	s_nop 0
	s_nop 0
	s_nop 0
	s_nop 0
	s_nop 0
	s_nop 0
	s_nop 0
	s_nop 0
	s_nop 0
	s_nop 0
	s_nop 0
	s_nop 0
	s_nop 0
	s_nop 0
	s_nop 0
	s_nop 0
	s_nop 0
	s_nop 0
	s_nop 0
	s_nop 0
	s_nop 0
	s_nop 0
	s_nop 0
	s_nop 0
	s_nop 0
	s_nop 0
	s_nop 0
	s_nop 0
	s_nop 0
	s_nop 0
	s_nop 0
	s_nop 0
	s_nop 0
	s_nop 0
	s_nop 0
	s_nop 0
	s_nop 0
	s_nop 0
	s_nop 0
	s_nop 0
	s_nop 0
	s_nop 0
	s_nop 0
	s_nop 0
	s_nop 0
	s_nop 0
	s_nop 0
	s_nop 0
	s_nop 0
	s_nop 0
	s_nop 0
	s_nop 0
	s_nop 0
	s_nop 0
	s_nop 0
	s_nop 0
	s_nop 0
	s_nop 0
	s_nop 0
	s_nop 0
	s_nop 0
	s_nop 0
	s_nop 0
	s_nop 0
	s_nop 0
	s_nop 0
	s_nop 0
	s_nop 0
	s_nop 0
	s_nop 0
	s_nop 0
	s_nop 0
	s_nop 0
	s_nop 0
	s_nop 0
	s_nop 0
	s_nop 0
	s_nop 0
	s_nop 0
	s_nop 0
	s_nop 0
	s_nop 0
	s_nop 0
	s_nop 0
	s_nop 0
	s_nop 0
	s_nop 0
	s_nop 0
	s_nop 0
	s_nop 0
	s_nop 0
	s_nop 0
	s_nop 0
	s_nop 0
	s_nop 0
	s_nop 0
	s_nop 0
	s_nop 0
	s_nop 0
	s_nop 0
	s_nop 0
	s_nop 0
	s_nop 0
	s_nop 0
	s_nop 0
	s_nop 0
	s_nop 0
	s_nop 0
	s_nop 0
	s_nop 0
	s_nop 0
	s_nop 0
	s_nop 0
	s_nop 0
	s_nop 0
	s_nop 0
	s_nop 0
	s_nop 0
	s_nop 0
	s_nop 0
	s_nop 0
	s_nop 0
	s_nop 0
	s_nop 0
	s_nop 0
	s_nop 0
	s_nop 0
	s_nop 0
	s_nop 0
	s_nop 0
	s_nop 0
	s_nop 0
	s_nop 0
